# P5 epilogue rewritten: post_g folded once, residual x rows fetched as full 1KB row segments (3 of 4 groups in flight right after the row-sum exchange), LDS rows pulled to registers so barriers do not
# speedup vs baseline: 1.0329x; 1.0053x over previous
; #define G_HALF(pl, ql, ps, qs, kt_) { const int k4_ = min((kt_) + 4, nk - 1); \
;         SB G_LOAD(pl, ql, k4_) F_LOAD(fa1, fb1, cur, 1) SB G_MFMA(fa0, fb0) SB G_STORE(ps, qs, wr) F_LOAD(fa0, fb0, nxt, 0) SB G_MFMA(fa1, fb1) SB \
;         __syncthreads(); { const int t_ = cur; cur = nxt; nxt = wr; wr = t_; } }
; #define G_HALF(pl, ql, ps, qs, kt_) { const int k4_ = min((kt_) + 4, nk - 1); \
;         SB R_BURST1(fb0, fb1, cur, 1, pl, ql, k4_, ps, qs, wr) R_BURST2(fb1, fb0, nxt, 0, ps, qs, wr) \
;         __syncthreads(); { const int t_ = cur; cur = nxt; nxt = wr; wr = t_; } }
; #define G_HALF(pl, ql, ps, qs, kt_) { const int k4_ = min((kt_) + 4, nk - 1); \
;         SB R_BURST1(fb0, fb1, cur, 1, pl, ql, k4_, ps, qs, wr) R_BURST2(fb1, fb0, nxt, 0, ps, qs, wr) \
;         __syncthreads(); { const int t_ = cur; cur = nxt; nxt = wr; wr = t_; } }
;     ...
; #pragma unroll 1
;     for (; kt + 3 <= nk; kt += 3) {
;         G_HALF(p1, q1, p2, q2, kt)
;         G_HALF(p2, q2, p0, q0, kt + 1)
;         G_HALF(p0, q0, p1, q1, kt + 2)
;     }
.LBB0_1060:
	s_waitcnt lgkmcnt(1)
	s_nop 0
	v_mfma_f32_32x32x16_bf16 v[112:127], v[180:183], v[160:163], v[112:127]
	ds_read_b128 v[218:221], v200 offset:22560
	s_waitcnt vmcnt(7)
	ds_write_b128 v205, v[156:159]
	s_waitcnt lgkmcnt(2)
	v_mfma_f32_32x32x16_bf16 v[48:63], v[180:183], v[164:167], v[48:63]
	global_load_dwordx4 v[180:183], v250, s[98:99] offset:256
	ds_read_b128 v[156:159], v198 offset:2080
	v_mfma_f32_32x32x16_bf16 v[96:111], v[176:179], v[160:163], v[96:111]
	ds_read_b128 v[222:225], v200 offset:25120
	s_waitcnt vmcnt(6)
	ds_write_b128 v204, v[152:155]
	v_mfma_f32_32x32x16_bf16 v[32:47], v[176:179], v[164:167], v[32:47]
	global_load_dwordx4 v[176:179], v251, s[98:99] offset:256
	ds_read_b128 v[152:155], v198 offset:4640
	v_mfma_f32_32x32x16_bf16 v[80:95], v[172:175], v[160:163], v[80:95]
	s_waitcnt vmcnt(5)
	ds_write_b128 v201, v[148:151]
	v_mfma_f32_32x32x16_bf16 v[16:31], v[172:175], v[164:167], v[16:31]
	global_load_dwordx4 v[172:175], v250, s[100:101] offset:256
	ds_read_b128 v[148:151], v198 offset:7200
	v_mfma_f32_32x32x16_bf16 v[64:79], v[168:171], v[160:163], v[64:79]
	s_waitcnt vmcnt(4)
	ds_write_b128 v203, v[144:147]
	v_mfma_f32_32x32x16_bf16 v[0:15], v[168:171], v[164:167], v[0:15]
	global_load_dwordx4 v[160:163], v251, s[100:101] offset:256
	ds_read_b128 v[144:147], v198 offset:9760
	s_waitcnt lgkmcnt(7)
	v_mfma_f32_32x32x16_bf16 v[112:127], v[156:159], v[218:221], v[112:127]
	ds_read_b128 v[164:167], v200 offset:63488
	s_waitcnt lgkmcnt(7)
	v_mfma_f32_32x32x16_bf16 v[48:63], v[156:159], v[222:225], v[48:63]
	ds_read_b128 v[156:159], v198 offset:43008
	s_waitcnt lgkmcnt(6)
	v_mfma_f32_32x32x16_bf16 v[96:111], v[152:155], v[218:221], v[96:111]
	ds_read_b128 v[168:171], v199 offset:43520
	v_mfma_f32_32x32x16_bf16 v[32:47], v[152:155], v[222:225], v[32:47]
	ds_read_b128 v[152:155], v198 offset:45568
	s_waitcnt lgkmcnt(6)
	v_mfma_f32_32x32x16_bf16 v[80:95], v[148:151], v[218:221], v[80:95]
	v_mfma_f32_32x32x16_bf16 v[16:31], v[148:151], v[222:225], v[16:31]
	ds_read_b128 v[148:151], v198 offset:48128
	s_waitcnt lgkmcnt(5)
	v_mfma_f32_32x32x16_bf16 v[64:79], v[144:147], v[218:221], v[64:79]
	v_mfma_f32_32x32x16_bf16 v[0:15], v[144:147], v[222:225], v[0:15]
	ds_read_b128 v[144:147], v198 offset:50688
	s_waitcnt lgkmcnt(0)
	s_barrier
	v_mfma_f32_32x32x16_bf16 v[112:127], v[156:159], v[164:167], v[112:127]
	ds_read_b128 v[218:221], v200 offset:63520
	ds_write_b128 v197, v[140:143] offset:2048
	v_mfma_f32_32x32x16_bf16 v[48:63], v[156:159], v[168:171], v[48:63]
	global_load_dwordx4 v[156:159], v250, s[98:99] offset:320
	ds_read_b128 v[140:143], v198 offset:43040
	v_mfma_f32_32x32x16_bf16 v[96:111], v[152:155], v[164:167], v[96:111]
	ds_read_b128 v[222:225], v199 offset:43552
	ds_write_b128 v197, v[136:139] offset:12288
	v_mfma_f32_32x32x16_bf16 v[32:47], v[152:155], v[168:171], v[32:47]
	global_load_dwordx4 v[152:155], v251, s[98:99] offset:320
	ds_read_b128 v[136:139], v198 offset:45600
	v_mfma_f32_32x32x16_bf16 v[80:95], v[148:151], v[164:167], v[80:95]
	ds_write_b128 v197, v[132:135] offset:22528
	v_mfma_f32_32x32x16_bf16 v[16:31], v[148:151], v[168:171], v[16:31]
	global_load_dwordx4 v[148:151], v250, s[100:101] offset:320
	ds_read_b128 v[132:135], v198 offset:48160
	v_mfma_f32_32x32x16_bf16 v[64:79], v[144:147], v[164:167], v[64:79]
	s_waitcnt vmcnt(7)
	ds_write_b128 v197, v[128:131] offset:32768
	v_mfma_f32_32x32x16_bf16 v[0:15], v[144:147], v[168:171], v[0:15]
	global_load_dwordx4 v[144:147], v251, s[100:101] offset:320
	ds_read_b128 v[128:131], v198 offset:50720
	s_waitcnt lgkmcnt(7)
	v_mfma_f32_32x32x16_bf16 v[112:127], v[140:143], v[218:221], v[112:127]
	ds_read_b128 v[164:167], v207
	s_waitcnt lgkmcnt(7)
	v_mfma_f32_32x32x16_bf16 v[48:63], v[140:143], v[222:225], v[48:63]
	ds_read_b128 v[140:143], v206
	s_waitcnt lgkmcnt(6)
	v_mfma_f32_32x32x16_bf16 v[96:111], v[136:139], v[218:221], v[96:111]
	ds_read_b128 v[168:171], v208
	v_mfma_f32_32x32x16_bf16 v[32:47], v[136:139], v[222:225], v[32:47]
	ds_read_b128 v[136:139], v209
	s_waitcnt lgkmcnt(6)
	v_mfma_f32_32x32x16_bf16 v[80:95], v[132:135], v[218:221], v[80:95]
	v_mfma_f32_32x32x16_bf16 v[16:31], v[132:135], v[222:225], v[16:31]
	ds_read_b128 v[132:135], v210
	s_waitcnt lgkmcnt(5)
	v_mfma_f32_32x32x16_bf16 v[64:79], v[128:131], v[218:221], v[64:79]
	v_mfma_f32_32x32x16_bf16 v[0:15], v[128:131], v[222:225], v[0:15]
	ds_read_b128 v[128:131], v211
	s_waitcnt lgkmcnt(0)
	s_barrier
	v_mfma_f32_32x32x16_bf16 v[112:127], v[140:143], v[164:167], v[112:127]
	ds_read_b128 v[218:221], v212
	s_waitcnt vmcnt(7)
	ds_write_b128 v197, v[180:183] offset:43008
	v_mfma_f32_32x32x16_bf16 v[48:63], v[140:143], v[168:171], v[48:63]
	global_load_dwordx4 v[140:143], v250, s[98:99] offset:384
	ds_read_b128 v[180:183], v213
	v_mfma_f32_32x32x16_bf16 v[96:111], v[136:139], v[164:167], v[96:111]
	ds_read_b128 v[222:225], v214
	s_waitcnt vmcnt(7)
	ds_write_b128 v197, v[176:179] offset:53248
	v_mfma_f32_32x32x16_bf16 v[32:47], v[136:139], v[168:171], v[32:47]
	ds_read_b128 v[176:179], v215
	global_load_dwordx4 v[136:139], v251, s[98:99] offset:384
	v_mfma_f32_32x32x16_bf16 v[80:95], v[132:135], v[164:167], v[80:95]
	s_waitcnt vmcnt(7)
	ds_write_b128 v197, v[172:175] offset:63488
	v_mfma_f32_32x32x16_bf16 v[16:31], v[132:135], v[168:171], v[16:31]
	global_load_dwordx4 v[132:135], v250, s[100:101] offset:384
	ds_read_b128 v[172:175], v216
	v_mfma_f32_32x32x16_bf16 v[64:79], v[128:131], v[164:167], v[64:79]
	s_waitcnt vmcnt(7)
	ds_write_b128 v202, v[160:163]
	v_mfma_f32_32x32x16_bf16 v[0:15], v[128:131], v[168:171], v[0:15]
	ds_read_b128 v[168:171], v217
	global_load_dwordx4 v[128:131], v251, s[100:101] offset:384
	s_waitcnt lgkmcnt(7)
	v_mfma_f32_32x32x16_bf16 v[112:127], v[180:183], v[218:221], v[112:127]
	ds_read_b128 v[160:163], v200 offset:22528
	s_waitcnt lgkmcnt(7)
	v_mfma_f32_32x32x16_bf16 v[48:63], v[180:183], v[222:225], v[48:63]
	ds_read_b128 v[180:183], v198 offset:2048
	s_waitcnt lgkmcnt(6)
	v_mfma_f32_32x32x16_bf16 v[96:111], v[176:179], v[218:221], v[96:111]
	ds_read_b128 v[164:167], v200 offset:25088
	v_mfma_f32_32x32x16_bf16 v[32:47], v[176:179], v[222:225], v[32:47]
	ds_read_b128 v[176:179], v198 offset:4608
	s_waitcnt lgkmcnt(6)
	v_mfma_f32_32x32x16_bf16 v[80:95], v[172:175], v[218:221], v[80:95]
	v_mfma_f32_32x32x16_bf16 v[16:31], v[172:175], v[222:225], v[16:31]
	ds_read_b128 v[172:175], v198 offset:7168
	s_waitcnt lgkmcnt(5)
	v_mfma_f32_32x32x16_bf16 v[64:79], v[168:171], v[218:221], v[64:79]
	v_mfma_f32_32x32x16_bf16 v[0:15], v[168:171], v[222:225], v[0:15]
	ds_read_b128 v[168:171], v198 offset:9728
	s_add_i32 s5, s5, 3
	v_add_u32_e32 v250, 0xc0, v250
	s_cmp_lt_u32 s5, 30
	v_add_u32_e32 v251, 0xc0, v251
	s_waitcnt lgkmcnt(0)
	s_barrier
; #define G_HALF(pl, ql, ps, qs, kt_) { const int k4_ = min((kt_) + 4, nk - 1); \
;         SB G_LOAD(pl, ql, k4_) F_LOAD(fa1, fb1, cur, 1) SB G_MFMA(fa0, fb0) SB G_STORE(ps, qs, wr) F_LOAD(fa0, fb0, nxt, 0) SB G_MFMA(fa1, fb1) SB \
;         __syncthreads(); { const int t_ = cur; cur = nxt; nxt = wr; wr = t_; } }
; #define G_HALF(pl, ql, ps, qs, kt_) { const int k4_ = min((kt_) + 4, nk - 1); \
;         SB R_BURST1(fb0, fb1, cur, 1, pl, ql, k4_, ps, qs, wr) R_BURST2(fb1, fb0, nxt, 0, ps, qs, wr) \
;         __syncthreads(); { const int t_ = cur; cur = nxt; nxt = wr; wr = t_; } }
; #define G_HALF(pl, ql, ps, qs, kt_) { const int k4_ = min((kt_) + 4, nk - 1); \
;         SB R_BURST1(fb0, fb1, cur, 1, pl, ql, k4_, ps, qs, wr) R_BURST2(fb1, fb0, nxt, 0, ps, qs, wr) \
;         __syncthreads(); { const int t_ = cur; cur = nxt; nxt = wr; wr = t_; } }
;     ...
;     if (kt < nk) G_HALF(p1, q1, p2, q2, kt)
;     if (kt + 1 < nk) G_HALF(p2, q2, p0, q0, kt + 1)
	s_cbranch_scc1 .LBB0_1060
	v_mfma_f32_32x32x16_bf16 v[112:127], v[180:183], v[160:163], v[112:127]
	ds_read_b128 v[186:189], v200 offset:22560
	s_waitcnt vmcnt(7)
	ds_write_b128 v205, v[156:159]
	v_mfma_f32_32x32x16_bf16 v[48:63], v[180:183], v[164:167], v[48:63]
	ds_read_b128 v[156:159], v198 offset:2080
	v_mfma_f32_32x32x16_bf16 v[96:111], v[176:179], v[160:163], v[96:111]
	ds_read_b128 v[180:183], v200 offset:25120
	s_waitcnt vmcnt(6)
	ds_write_b128 v204, v[152:155]
	v_mfma_f32_32x32x16_bf16 v[32:47], v[176:179], v[164:167], v[32:47]
	ds_read_b128 v[152:155], v198 offset:4640
	v_mfma_f32_32x32x16_bf16 v[80:95], v[172:175], v[160:163], v[80:95]
	s_waitcnt vmcnt(5)
	ds_write_b128 v201, v[148:151]
	v_mfma_f32_32x32x16_bf16 v[16:31], v[172:175], v[164:167], v[16:31]
	ds_read_b128 v[148:151], v198 offset:7200
	v_mfma_f32_32x32x16_bf16 v[64:79], v[168:171], v[160:163], v[64:79]
	s_waitcnt vmcnt(4)
	ds_write_b128 v203, v[144:147]
	v_mfma_f32_32x32x16_bf16 v[0:15], v[168:171], v[164:167], v[0:15]
	ds_read_b128 v[144:147], v198 offset:9760
	s_waitcnt lgkmcnt(7)
	v_mfma_f32_32x32x16_bf16 v[112:127], v[156:159], v[186:189], v[112:127]
	ds_read_b128 v[160:163], v200 offset:63488
	s_waitcnt lgkmcnt(7)
	v_mfma_f32_32x32x16_bf16 v[48:63], v[156:159], v[180:183], v[48:63]
	ds_read_b128 v[156:159], v198 offset:43008
	s_waitcnt lgkmcnt(6)
	v_mfma_f32_32x32x16_bf16 v[96:111], v[152:155], v[186:189], v[96:111]
	ds_read_b128 v[164:167], v199 offset:43520
	v_mfma_f32_32x32x16_bf16 v[32:47], v[152:155], v[180:183], v[32:47]
	ds_read_b128 v[152:155], v198 offset:45568
	s_waitcnt lgkmcnt(6)
	v_mfma_f32_32x32x16_bf16 v[80:95], v[148:151], v[186:189], v[80:95]
	v_mfma_f32_32x32x16_bf16 v[16:31], v[148:151], v[180:183], v[16:31]
	ds_read_b128 v[148:151], v198 offset:48128
	s_waitcnt lgkmcnt(5)
	v_mfma_f32_32x32x16_bf16 v[64:79], v[144:147], v[186:189], v[64:79]
	v_mfma_f32_32x32x16_bf16 v[0:15], v[144:147], v[180:183], v[0:15]
	ds_read_b128 v[144:147], v198 offset:50688
	s_waitcnt lgkmcnt(0)
	s_barrier
; DI void phase5(const Params& p, unsigned char* smem, int tid, bool coop) {
;     ...
; #pragma unroll
;         for (int jt = 0; jt < 2; ++jt) {
;             const int tr = tt * 256 + wj * 64 + jt * 32 + ln;
;             float sq = 0.f;
; #pragma unroll
;             for (int it = 0; it < 4; ++it)
; #pragma unroll
;                 for (int r = 0; r < 16; ++r) sq += acc[it][jt][r] * acc[it][jt][r];
;             { const auto sw = __builtin_amdgcn_permlane32_swap(__float_as_uint(sq), __float_as_uint(sq), false, false);
;               sq = __uint_as_float(sw[0]) + __uint_as_float(sw[1]); }
;             if (h == 0) atomicAdd(ssq + tr, sq);
;         }
;     ...
;                 [&](int it, int jt, int g) { const f32x4 gv = *(const f32x4*)(p.post_g + f * 256 + wi * 128 + it * 32 + 8 * g + 4 * h); const float rs = rsj[jt];
	v_mfma_f32_32x32x16_bf16 v[112:127], v[156:159], v[160:163], v[112:127]
	ds_read_b128 v[168:171], v200 offset:63520
	s_waitcnt vmcnt(3)
	ds_write_b128 v197, v[140:143] offset:2048
	v_mfma_f32_32x32x16_bf16 v[48:63], v[156:159], v[164:167], v[48:63]
	ds_read_b128 v[140:143], v198 offset:43040
	v_mfma_f32_32x32x16_bf16 v[96:111], v[152:155], v[160:163], v[96:111]
	ds_read_b128 v[156:159], v199 offset:43552
	s_waitcnt vmcnt(2)
	ds_write_b128 v197, v[136:139] offset:12288
	v_mfma_f32_32x32x16_bf16 v[32:47], v[152:155], v[164:167], v[32:47]
	ds_read_b128 v[136:139], v198 offset:45600
	v_mfma_f32_32x32x16_bf16 v[80:95], v[148:151], v[160:163], v[80:95]
	s_waitcnt vmcnt(1)
	ds_write_b128 v197, v[132:135] offset:22528
	v_mfma_f32_32x32x16_bf16 v[16:31], v[148:151], v[164:167], v[16:31]
	ds_read_b128 v[132:135], v198 offset:48160
	v_mfma_f32_32x32x16_bf16 v[64:79], v[144:147], v[160:163], v[64:79]
	s_waitcnt vmcnt(0)
	ds_write_b128 v197, v[128:131] offset:32768
	v_mfma_f32_32x32x16_bf16 v[0:15], v[144:147], v[164:167], v[0:15]
	ds_read_b128 v[128:131], v198 offset:50720
	s_waitcnt lgkmcnt(7)
	v_mfma_f32_32x32x16_bf16 v[112:127], v[140:143], v[168:171], v[112:127]
	s_waitcnt lgkmcnt(6)
	v_mfma_f32_32x32x16_bf16 v[48:63], v[140:143], v[156:159], v[48:63]
	s_waitcnt lgkmcnt(4)
	v_mfma_f32_32x32x16_bf16 v[96:111], v[136:139], v[168:171], v[96:111]
	v_mfma_f32_32x32x16_bf16 v[32:47], v[136:139], v[156:159], v[32:47]
	s_waitcnt lgkmcnt(2)
	v_mfma_f32_32x32x16_bf16 v[80:95], v[132:135], v[168:171], v[80:95]
	v_mfma_f32_32x32x16_bf16 v[16:31], v[132:135], v[156:159], v[16:31]
	s_waitcnt lgkmcnt(0)
	v_mfma_f32_32x32x16_bf16 v[64:79], v[128:131], v[168:171], v[64:79]
	v_mfma_f32_32x32x16_bf16 v[0:15], v[128:131], v[156:159], v[0:15]
	v_readfirstlane_b32 s98, v194
	v_ashrrev_i32_e32 v252, 8, v194
	v_bfe_u32 v253, v194, 5, 1
	v_lshlrev_b32_e32 v252, 9, v252
	v_lshl_add_u32 v252, v253, 4, v252
	s_lshl_b32 s99, s53, 10
	s_add_u32 s36, s8, s99
	s_addc_u32 s37, s9, 0
	s_add_u32 s100, s26, s99
	s_addc_u32 s101, s27, 0
	global_load_dwordx4 v[146:149], v252, s[36:37]
	global_load_dwordx4 v[150:153], v252, s[36:37] offset:32
	global_load_dwordx4 v[154:157], v252, s[36:37] offset:64
	global_load_dwordx4 v[158:161], v252, s[36:37] offset:96
	global_load_dwordx4 v[162:165], v252, s[36:37] offset:128
	global_load_dwordx4 v[166:169], v252, s[36:37] offset:160
	global_load_dwordx4 v[170:173], v252, s[36:37] offset:192
	global_load_dwordx4 v[174:177], v252, s[36:37] offset:224
	global_load_dwordx4 v[178:181], v252, s[36:37] offset:256
	global_load_dwordx4 v[186:189], v252, s[36:37] offset:288
	global_load_dwordx4 v[190:193], v252, s[36:37] offset:320
	global_load_dwordx4 v[198:201], v252, s[36:37] offset:352
	global_load_dwordx4 v[202:205], v252, s[36:37] offset:384
	global_load_dwordx4 v[206:209], v252, s[36:37] offset:416
	global_load_dwordx4 v[210:213], v252, s[36:37] offset:448
	global_load_dwordx4 v[214:217], v252, s[36:37] offset:480
	v_lshrrev_b32_e32 v254, 7, v194
	v_lshlrev_b32_e32 v254, 18, v254
	v_bfe_u32 v253, v194, 6, 1
	v_lshl_add_u32 v254, v253, 16, v254
	v_and_b32_e32 v253, 63, v194
	v_lshl_add_u32 v254, v253, 4, v254
	s_lshl_b32 s99, s30, 12
	v_add_u32_e32 v254, s99, v254
	v_lshrrev_b32_e32 v246, 6, v194
	v_mul_u32_u24_e32 v246, 0x2100, v246
	v_lshl_add_u32 v246, v253, 3, v246
	s_nop 0
	v_mul_f32_e32 v128, v113, v113
	v_fmac_f32_e32 v128, v112, v112
	v_fmac_f32_e32 v128, v114, v114
	v_fmac_f32_e32 v128, v115, v115
	v_fmac_f32_e32 v128, v116, v116
	v_fmac_f32_e32 v128, v117, v117
	v_fmac_f32_e32 v128, v118, v118
	v_fmac_f32_e32 v128, v119, v119
	v_fmac_f32_e32 v128, v120, v120
	v_fmac_f32_e32 v128, v121, v121
	v_fmac_f32_e32 v128, v122, v122
	v_fmac_f32_e32 v128, v123, v123
	v_fmac_f32_e32 v128, v124, v124
	v_fmac_f32_e32 v128, v125, v125
	v_fmac_f32_e32 v128, v126, v126
	v_fmac_f32_e32 v128, v127, v127
	v_fmac_f32_e32 v128, v96, v96
	v_fmac_f32_e32 v128, v97, v97
	v_fmac_f32_e32 v128, v98, v98
	v_fmac_f32_e32 v128, v99, v99
	v_fmac_f32_e32 v128, v100, v100
	v_fmac_f32_e32 v128, v101, v101
	v_fmac_f32_e32 v128, v102, v102
	v_fmac_f32_e32 v128, v103, v103
	v_fmac_f32_e32 v128, v104, v104
	v_fmac_f32_e32 v128, v105, v105
	v_fmac_f32_e32 v128, v106, v106
	v_fmac_f32_e32 v128, v107, v107
	v_fmac_f32_e32 v128, v108, v108
	v_fmac_f32_e32 v128, v109, v109
	v_fmac_f32_e32 v128, v110, v110
	v_fmac_f32_e32 v128, v111, v111
	v_fmac_f32_e32 v128, v80, v80
	v_fmac_f32_e32 v128, v81, v81
	v_fmac_f32_e32 v128, v82, v82
	v_fmac_f32_e32 v128, v83, v83
	v_fmac_f32_e32 v128, v84, v84
	v_fmac_f32_e32 v128, v85, v85
	v_fmac_f32_e32 v128, v86, v86
	v_fmac_f32_e32 v128, v87, v87
	v_fmac_f32_e32 v128, v88, v88
	v_fmac_f32_e32 v128, v89, v89
	v_fmac_f32_e32 v128, v90, v90
	v_fmac_f32_e32 v128, v91, v91
	v_fmac_f32_e32 v128, v92, v92
	v_fmac_f32_e32 v128, v93, v93
	v_fmac_f32_e32 v128, v94, v94
	v_fmac_f32_e32 v128, v95, v95
	v_fmac_f32_e32 v128, v64, v64
	v_fmac_f32_e32 v128, v65, v65
	v_fmac_f32_e32 v128, v66, v66
	v_fmac_f32_e32 v128, v67, v67
	v_fmac_f32_e32 v128, v68, v68
	v_fmac_f32_e32 v128, v69, v69
	v_fmac_f32_e32 v128, v70, v70
	v_fmac_f32_e32 v128, v71, v71
	v_fmac_f32_e32 v128, v72, v72
	v_fmac_f32_e32 v128, v73, v73
	v_fmac_f32_e32 v128, v74, v74
	v_fmac_f32_e32 v128, v75, v75
	v_fmac_f32_e32 v128, v76, v76
	v_fmac_f32_e32 v128, v77, v77
	v_mov_b32_e32 v142, v194
	v_fmac_f32_e32 v128, v78, v78
	s_barrier
	v_fmac_f32_e32 v128, v79, v79
	v_and_b32_e32 v134, 0xc0, v142
	v_and_b32_e32 v143, 31, v142
	v_bfe_u32 v129, v142, 5, 1
	v_or3_b32 v130, v134, s30, v143
	v_mov_b32_e32 v132, v128
	v_cmp_eq_u32_e32 vcc, 0, v129
	s_nop 0
	v_permlane32_swap_b32_e32 v128, v132
	v_ashrrev_i32_e32 v131, 31, v130
	s_and_saveexec_b64 s[6:7], vcc
	s_cbranch_execz .LBB0_1063
	v_add_f32_e32 v128, v128, v132
	v_lshl_add_u64 v[132:133], v[130:131], 2, s[18:19]
	global_atomic_add_f32 v[132:133], v128, off

; DI u32x2 pk4(float a, float b, float c, float d) { u32x2 r; r.x = pk2(a, b); r.y = pk2(c, d); return r; }
; template <int WI, int WGJ, class GetF, class LdF, class FinF>
; DI void staged_rows_rmw(unsigned char* lds, int tid, GetF get, LdF ld, FinF fin) {
;     ...
;         for (int gq = 0; gq < NGRP; ++gq) {
;             decltype(ld(0, 0)) fetched[GSZ];
; #pragma unroll
;             for (int c = 0; c < GSZ; ++c) {
;                 const int idx = tid + (gq * GSZ + c) * NT, lr = idx / NCH, ch = idx % NCH;
;                 fetched[c] = ld((lr >> 5) * 64 + jt * 32 + (lr & 31), ch * 8);
;             }
; DI void phase5(const Params& p, unsigned char* smem, int tid, bool coop) {
;     ...
;             float rsj[2];
; #pragma unroll
;             for (int jt = 0; jt < 2; ++jt)
;                 rsj[jt] = 1.0f / sqrtf(__hip_atomic_load(ssq + tt * 256 + wj * 64 + jt * 32 + ln, __ATOMIC_RELAXED, __HIP_MEMORY_SCOPE_AGENT) * (1.0f / D) + EPS);
;             staged_rows_rmw<4, 4>(lds, te,
;                 [&](int it, int jt, int g) { const f32x4 gv = *(const f32x4*)(p.post_g + f * 256 + wi * 128 + it * 32 + 8 * g + 4 * h); const float rs = rsj[jt];
;                     return pk4(acc[it][jt][4 * g] * rs * gv[0], acc[it][jt][4 * g + 1] * rs * gv[1], acc[it][jt][4 * g + 2] * rs * gv[2], acc[it][jt][4 * g + 3] * rs * gv[3]); },
;                 [&](int row, int col) { const size_t o = (size_t)(tt * 256 + row) * 1024 + f * 256 + col; X8 r; r.a = __builtin_nontemporal_load((const f32x4*)(p.x + o)); r.b = __builtin_nontemporal_load((const f32x4*)(p.x + o + 4)); return r; },
.LBB0_1084:
	s_or_b64 exec, exec, s[6:7]
	s_lshl_b32 s99, s53, 10
	s_add_u32 s6, s10, s99
	s_addc_u32 s7, s11, 0
	v_pk_mul_f32 v[112:113], v[112:113], v[146:147]
	v_pk_mul_f32 v[114:115], v[114:115], v[148:149]
	v_pk_mul_f32 v[48:49], v[48:49], v[146:147]
	v_pk_mul_f32 v[50:51], v[50:51], v[148:149]
	v_pk_mul_f32 v[116:117], v[116:117], v[150:151]
	v_pk_mul_f32 v[118:119], v[118:119], v[152:153]
	v_pk_mul_f32 v[52:53], v[52:53], v[150:151]
	v_pk_mul_f32 v[54:55], v[54:55], v[152:153]
	v_pk_mul_f32 v[120:121], v[120:121], v[154:155]
	v_pk_mul_f32 v[122:123], v[122:123], v[156:157]
	v_pk_mul_f32 v[56:57], v[56:57], v[154:155]
	v_pk_mul_f32 v[58:59], v[58:59], v[156:157]
	v_pk_mul_f32 v[124:125], v[124:125], v[158:159]
	v_pk_mul_f32 v[126:127], v[126:127], v[160:161]
	v_pk_mul_f32 v[60:61], v[60:61], v[158:159]
	v_pk_mul_f32 v[62:63], v[62:63], v[160:161]
	v_pk_mul_f32 v[96:97], v[96:97], v[162:163]
	v_pk_mul_f32 v[98:99], v[98:99], v[164:165]
	v_pk_mul_f32 v[32:33], v[32:33], v[162:163]
	v_pk_mul_f32 v[34:35], v[34:35], v[164:165]
	v_pk_mul_f32 v[100:101], v[100:101], v[166:167]
	v_pk_mul_f32 v[102:103], v[102:103], v[168:169]
	v_pk_mul_f32 v[36:37], v[36:37], v[166:167]
	v_pk_mul_f32 v[38:39], v[38:39], v[168:169]
	v_pk_mul_f32 v[104:105], v[104:105], v[170:171]
	v_pk_mul_f32 v[106:107], v[106:107], v[172:173]
	v_pk_mul_f32 v[40:41], v[40:41], v[170:171]
	v_pk_mul_f32 v[42:43], v[42:43], v[172:173]
	v_pk_mul_f32 v[108:109], v[108:109], v[174:175]
	v_pk_mul_f32 v[110:111], v[110:111], v[176:177]
	v_pk_mul_f32 v[44:45], v[44:45], v[174:175]
	v_pk_mul_f32 v[46:47], v[46:47], v[176:177]
	v_pk_mul_f32 v[80:81], v[80:81], v[178:179]
	v_pk_mul_f32 v[82:83], v[82:83], v[180:181]
	v_pk_mul_f32 v[16:17], v[16:17], v[178:179]
	v_pk_mul_f32 v[18:19], v[18:19], v[180:181]
	v_pk_mul_f32 v[84:85], v[84:85], v[186:187]
	v_pk_mul_f32 v[86:87], v[86:87], v[188:189]
	v_pk_mul_f32 v[20:21], v[20:21], v[186:187]
	v_pk_mul_f32 v[22:23], v[22:23], v[188:189]
	v_pk_mul_f32 v[88:89], v[88:89], v[190:191]
	v_pk_mul_f32 v[90:91], v[90:91], v[192:193]
	v_pk_mul_f32 v[24:25], v[24:25], v[190:191]
	v_pk_mul_f32 v[26:27], v[26:27], v[192:193]
	v_pk_mul_f32 v[92:93], v[92:93], v[198:199]
	v_pk_mul_f32 v[94:95], v[94:95], v[200:201]
	v_pk_mul_f32 v[28:29], v[28:29], v[198:199]
	v_pk_mul_f32 v[30:31], v[30:31], v[200:201]
	v_pk_mul_f32 v[64:65], v[64:65], v[202:203]
	v_pk_mul_f32 v[66:67], v[66:67], v[204:205]
	v_pk_mul_f32 v[0:1], v[0:1], v[202:203]
	v_pk_mul_f32 v[2:3], v[2:3], v[204:205]
	v_pk_mul_f32 v[68:69], v[68:69], v[206:207]
	v_pk_mul_f32 v[70:71], v[70:71], v[208:209]
	v_pk_mul_f32 v[4:5], v[4:5], v[206:207]
	v_pk_mul_f32 v[6:7], v[6:7], v[208:209]
	v_pk_mul_f32 v[72:73], v[72:73], v[210:211]
	v_pk_mul_f32 v[74:75], v[74:75], v[212:213]
	v_pk_mul_f32 v[8:9], v[8:9], v[210:211]
	v_pk_mul_f32 v[10:11], v[10:11], v[212:213]
	v_pk_mul_f32 v[76:77], v[76:77], v[214:215]
	v_pk_mul_f32 v[78:79], v[78:79], v[216:217]
	v_pk_mul_f32 v[12:13], v[12:13], v[214:215]
	v_pk_mul_f32 v[14:15], v[14:15], v[216:217]
	s_lshl_b32 s99, s30, 2
	s_add_u32 s36, s18, s99
	s_addc_u32 s37, s19, 0
	v_add_u32_e32 v252, v134, v143
	v_lshlrev_b32_e32 v252, 2, v252
	s_barrier
	global_load_dword v144, v252, s[36:37] sc1
	global_load_dword v145, v252, s[36:37] offset:128 sc1
	v_add_u32_e32 v252, 0x1000, v254
	global_load_dwordx4 v[218:221], v252, s[100:101] offset:-4096 nt
	global_load_dwordx4 v[222:225], v252, s[100:101] nt
	v_add_u32_e32 v253, 0x3000, v254
	global_load_dwordx4 v[226:229], v253, s[100:101] offset:-4096 nt
	global_load_dwordx4 v[230:233], v253, s[100:101] nt
	v_add_u32_e32 v252, 0x5000, v254
	global_load_dwordx4 v[234:237], v252, s[100:101] offset:-4096 nt
	global_load_dwordx4 v[238:241], v252, s[100:101] nt
	v_add_u32_e32 v253, 0x7000, v254
	global_load_dwordx4 v[242:245], v253, s[100:101] offset:-4096 nt
	global_load_dwordx4 v[248:251], v253, s[100:101] nt
	v_add_u32_e32 v252, 0x9000, v254
	global_load_dwordx4 v[146:149], v252, s[100:101] offset:-4096 nt
	global_load_dwordx4 v[150:153], v252, s[100:101] nt
	v_add_u32_e32 v253, 0xb000, v254
	global_load_dwordx4 v[154:157], v253, s[100:101] offset:-4096 nt
	global_load_dwordx4 v[158:161], v253, s[100:101] nt
	v_add_u32_e32 v252, 0xd000, v254
	global_load_dwordx4 v[162:165], v252, s[100:101] offset:-4096 nt
	global_load_dwordx4 v[166:169], v252, s[100:101] nt
	v_add_u32_e32 v253, 0xf000, v254
	global_load_dwordx4 v[170:173], v253, s[100:101] offset:-4096 nt
	global_load_dwordx4 v[174:177], v253, s[100:101] nt
	v_add_u32_e32 v252, 0x21000, v254
	global_load_dwordx4 v[178:181], v252, s[100:101] offset:-4096 nt
	global_load_dwordx4 v[186:189], v252, s[100:101] nt
	v_add_u32_e32 v253, 0x23000, v254
	global_load_dwordx4 v[190:193], v253, s[100:101] offset:-4096 nt
	global_load_dwordx4 v[198:201], v253, s[100:101] nt
	v_add_u32_e32 v252, 0x25000, v254
	global_load_dwordx4 v[202:205], v252, s[100:101] offset:-4096 nt
	global_load_dwordx4 v[206:209], v252, s[100:101] nt
	v_add_u32_e32 v253, 0x27000, v254
	global_load_dwordx4 v[210:213], v253, s[100:101] offset:-4096 nt
	global_load_dwordx4 v[214:217], v253, s[100:101] nt
	v_lshrrev_b32_e32 v128, 6, v142
	v_and_b32_e32 v129, 3, v128
	v_lshrrev_b32_e32 v128, 2, v128
	v_lshl_or_b32 v129, v129, 5, v143
	v_mul_u32_u24_e32 v129, 0x210, v129
	v_lshl_add_u32 v129, v128, 8, v129
	v_lshrrev_b32_e32 v128, 2, v142
	v_and_b32_e32 v128, 8, v128
	v_add_u32_e32 v129, v129, v128
	v_add_u32_e32 v143, 0x800, v129
	s_waitcnt vmcnt(24)
; DI u32x2 pk4(float a, float b, float c, float d) { u32x2 r; r.x = pk2(a, b); r.y = pk2(c, d); return r; }
; template <int WI, int WGJ, class GetF, class LdF, class FinF>
; DI void staged_rows_rmw(unsigned char* lds, int tid, GetF get, LdF ld, FinF fin) {
;     ...
;     for (int jt = 0; jt < 2; ++jt) {
;         unsigned char* wrow = lds + (wj * 32 + ln) * RS + (wi * WI * 32 + 4 * h) * 2;
; #pragma unroll
;         for (int it = 0; it < WI; ++it)
; #pragma unroll
;             for (int g = 0; g < 4; ++g) *(u32x2*)(wrow + (it * 32 + 8 * g) * 2) = get(it, jt, g);
;         constexpr int NGRP = 2, GSZ = NIT / NGRP;
;         __syncthreads();
; DI void phase5(const Params& p, unsigned char* smem, int tid, bool coop) {
;     ...
;             float rsj[2];
; #pragma unroll
;             for (int jt = 0; jt < 2; ++jt)
;                 rsj[jt] = 1.0f / sqrtf(__hip_atomic_load(ssq + tt * 256 + wj * 64 + jt * 32 + ln, __ATOMIC_RELAXED, __HIP_MEMORY_SCOPE_AGENT) * (1.0f / D) + EPS);
;             staged_rows_rmw<4, 4>(lds, te,
;                 [&](int it, int jt, int g) { const f32x4 gv = *(const f32x4*)(p.post_g + f * 256 + wi * 128 + it * 32 + 8 * g + 4 * h); const float rs = rsj[jt];
;                     return pk4(acc[it][jt][4 * g] * rs * gv[0], acc[it][jt][4 * g + 1] * rs * gv[1], acc[it][jt][4 * g + 2] * rs * gv[2], acc[it][jt][4 * g + 3] * rs * gv[3]); },
	v_fmamk_f32 v144, v144, 0x3a800000, v195
	v_fmamk_f32 v145, v145, 0x3a800000, v195
	v_mul_f32_e32 v182, 0x4f800000, v144
	v_cmp_gt_f32_e32 vcc, s49, v144
	v_mul_f32_e32 v183, 0x4f800000, v145
	v_cmp_gt_f32_e64 s[38:39], s49, v145
	v_cndmask_b32_e32 v144, v144, v182, vcc
	v_sqrt_f32_e32 v182, v144
	v_cndmask_b32_e64 v145, v145, v183, s[38:39]
	v_sqrt_f32_e32 v183, v145
	v_add_u32_e32 v184, -1, v182
	v_fma_f32 v130, -v184, v182, v144
	v_add_u32_e32 v128, -1, v183
	v_add_u32_e32 v197, 1, v182
	v_fma_f32 v132, -v128, v183, v145
	v_cmp_ge_f32_e64 s[36:37], 0, v130
	v_add_u32_e32 v129, 1, v183
	v_fma_f32 v131, -v197, v182, v144
	v_cndmask_b32_e64 v182, v182, v184, s[36:37]
	v_cmp_ge_f32_e64 s[36:37], 0, v132
	v_fma_f32 v133, -v129, v183, v145
	s_nop 0
	v_cndmask_b32_e64 v183, v183, v128, s[36:37]
	v_cmp_lt_f32_e64 s[36:37], 0, v131
	s_nop 1
	v_cndmask_b32_e64 v182, v182, v197, s[36:37]
	v_cmp_lt_f32_e64 s[36:37], 0, v133
	v_mul_f32_e32 v184, 0x37800000, v182
	v_cndmask_b32_e32 v182, v182, v184, vcc
	v_cndmask_b32_e64 v183, v183, v129, s[36:37]
	v_cmp_class_f32_e32 vcc, v144, v196
	v_mul_f32_e32 v197, 0x37800000, v183
	v_cndmask_b32_e64 v183, v183, v197, s[38:39]
	v_cndmask_b32_e32 v182, v182, v144, vcc
	v_div_scale_f32 v184, s[38:39], v182, v182, 1.0
	v_rcp_f32_e32 v197, v184
	v_cmp_class_f32_e32 vcc, v145, v196
	s_nop 1
	v_cndmask_b32_e32 v144, v183, v145, vcc
	v_fma_f32 v183, -v184, v197, 1.0
	v_div_scale_f32 v145, vcc, 1.0, v182, 1.0
	v_fmac_f32_e32 v197, v183, v197
	v_mul_f32_e32 v183, v145, v197
	v_fma_f32 v128, -v184, v183, v145
	v_fmac_f32_e32 v183, v128, v197
	v_fma_f32 v145, -v184, v183, v145
	v_div_fmas_f32 v145, v145, v197, v183
	v_div_fixup_f32 v182, v145, v182, 1.0
	v_div_scale_f32 v128, s[34:35], v144, v144, 1.0
	v_rcp_f32_e32 v130, v128
	v_div_scale_f32 v129, vcc, 1.0, v144, 1.0
	v_fma_f32 v131, -v128, v130, 1.0
	v_fmac_f32_e32 v130, v131, v130
	v_mul_f32_e32 v131, v129, v130
	v_fma_f32 v132, -v128, v131, v129
	v_fmac_f32_e32 v131, v132, v130
	v_fma_f32 v128, -v128, v131, v129
	v_div_fmas_f32 v128, v128, v130, v131
	v_div_fixup_f32 v144, v128, v144, 1.0
	v_pk_mul_f32 v[112:113], v[112:113], v[182:183] op_sel_hi:[1,0]
	v_pk_mul_f32 v[114:115], v[114:115], v[182:183] op_sel_hi:[1,0]
	v_pk_mul_f32 v[116:117], v[116:117], v[182:183] op_sel_hi:[1,0]
	v_pk_mul_f32 v[118:119], v[118:119], v[182:183] op_sel_hi:[1,0]
	v_pk_mul_f32 v[120:121], v[120:121], v[182:183] op_sel_hi:[1,0]
	v_pk_mul_f32 v[122:123], v[122:123], v[182:183] op_sel_hi:[1,0]
	v_pk_mul_f32 v[124:125], v[124:125], v[182:183] op_sel_hi:[1,0]
	v_pk_mul_f32 v[126:127], v[126:127], v[182:183] op_sel_hi:[1,0]
	v_pk_mul_f32 v[96:97], v[96:97], v[182:183] op_sel_hi:[1,0]
	v_pk_mul_f32 v[98:99], v[98:99], v[182:183] op_sel_hi:[1,0]
	v_pk_mul_f32 v[100:101], v[100:101], v[182:183] op_sel_hi:[1,0]
	v_pk_mul_f32 v[102:103], v[102:103], v[182:183] op_sel_hi:[1,0]
	v_pk_mul_f32 v[104:105], v[104:105], v[182:183] op_sel_hi:[1,0]
	v_pk_mul_f32 v[106:107], v[106:107], v[182:183] op_sel_hi:[1,0]
	v_pk_mul_f32 v[108:109], v[108:109], v[182:183] op_sel_hi:[1,0]
	v_pk_mul_f32 v[110:111], v[110:111], v[182:183] op_sel_hi:[1,0]
	v_pk_mul_f32 v[80:81], v[80:81], v[182:183] op_sel_hi:[1,0]
	v_pk_mul_f32 v[82:83], v[82:83], v[182:183] op_sel_hi:[1,0]
	v_pk_mul_f32 v[84:85], v[84:85], v[182:183] op_sel_hi:[1,0]
	v_pk_mul_f32 v[86:87], v[86:87], v[182:183] op_sel_hi:[1,0]
	v_pk_mul_f32 v[88:89], v[88:89], v[182:183] op_sel_hi:[1,0]
	v_pk_mul_f32 v[90:91], v[90:91], v[182:183] op_sel_hi:[1,0]
	v_pk_mul_f32 v[92:93], v[92:93], v[182:183] op_sel_hi:[1,0]
	v_pk_mul_f32 v[94:95], v[94:95], v[182:183] op_sel_hi:[1,0]
	v_pk_mul_f32 v[64:65], v[64:65], v[182:183] op_sel_hi:[1,0]
	v_pk_mul_f32 v[66:67], v[66:67], v[182:183] op_sel_hi:[1,0]
	v_pk_mul_f32 v[68:69], v[68:69], v[182:183] op_sel_hi:[1,0]
	v_pk_mul_f32 v[70:71], v[70:71], v[182:183] op_sel_hi:[1,0]
	v_pk_mul_f32 v[72:73], v[72:73], v[182:183] op_sel_hi:[1,0]
	v_pk_mul_f32 v[74:75], v[74:75], v[182:183] op_sel_hi:[1,0]
	v_pk_mul_f32 v[76:77], v[76:77], v[182:183] op_sel_hi:[1,0]
	v_pk_mul_f32 v[78:79], v[78:79], v[182:183] op_sel_hi:[1,0]
	v_cvt_pk_bf16_f32 v112, v112, v113
	v_cvt_pk_bf16_f32 v113, v114, v115
	v_cvt_pk_bf16_f32 v116, v116, v117
	v_cvt_pk_bf16_f32 v117, v118, v119
	v_cvt_pk_bf16_f32 v120, v120, v121
	v_cvt_pk_bf16_f32 v121, v122, v123
	v_cvt_pk_bf16_f32 v124, v124, v125
	v_cvt_pk_bf16_f32 v125, v126, v127
	v_cvt_pk_bf16_f32 v96, v96, v97
	v_cvt_pk_bf16_f32 v97, v98, v99
	v_cvt_pk_bf16_f32 v100, v100, v101
	v_cvt_pk_bf16_f32 v101, v102, v103
	v_cvt_pk_bf16_f32 v104, v104, v105
	v_cvt_pk_bf16_f32 v105, v106, v107
	v_cvt_pk_bf16_f32 v108, v108, v109
	v_cvt_pk_bf16_f32 v109, v110, v111
	v_cvt_pk_bf16_f32 v80, v80, v81
	v_cvt_pk_bf16_f32 v81, v82, v83
	v_cvt_pk_bf16_f32 v84, v84, v85
	v_cvt_pk_bf16_f32 v85, v86, v87
	v_cvt_pk_bf16_f32 v88, v88, v89
	v_cvt_pk_bf16_f32 v89, v90, v91
	v_cvt_pk_bf16_f32 v92, v92, v93
	v_cvt_pk_bf16_f32 v93, v94, v95
	v_cvt_pk_bf16_f32 v64, v64, v65
	v_cvt_pk_bf16_f32 v65, v66, v67
	v_cvt_pk_bf16_f32 v68, v68, v69
	v_cvt_pk_bf16_f32 v69, v70, v71
	v_cvt_pk_bf16_f32 v72, v72, v73
	v_cvt_pk_bf16_f32 v73, v74, v75
	v_cvt_pk_bf16_f32 v76, v76, v77
	v_cvt_pk_bf16_f32 v77, v78, v79
	ds_write2_b64 v143, v[112:113], v[116:117] offset0:0 offset1:2
	ds_write2_b64 v143, v[120:121], v[124:125] offset0:4 offset1:6
	ds_write2_b64 v143, v[96:97], v[100:101] offset0:8 offset1:10
	ds_write2_b64 v143, v[104:105], v[108:109] offset0:12 offset1:14
	ds_write2_b64 v143, v[80:81], v[84:85] offset0:16 offset1:18
	ds_write2_b64 v143, v[88:89], v[92:93] offset0:20 offset1:22
	ds_write2_b64 v143, v[64:65], v[68:69] offset0:24 offset1:26
	ds_write2_b64 v143, v[72:73], v[76:77] offset0:28 offset1:30
	s_waitcnt lgkmcnt(0)
	s_barrier
; template <int WI, int WGJ, class GetF, class LdF, class FinF>
; DI void staged_rows_rmw(unsigned char* lds, int tid, GetF get, LdF ld, FinF fin) {
;     ...
; #pragma unroll
;     for (int jt = 0; jt < 2; ++jt) {
;         unsigned char* wrow = lds + (wj * 32 + ln) * RS + (wi * WI * 32 + 4 * h) * 2;
; #pragma unroll
;         for (int it = 0; it < WI; ++it)
; #pragma unroll
;             for (int g = 0; g < 4; ++g) *(u32x2*)(wrow + (it * 32 + 8 * g) * 2) = get(it, jt, g);
;         constexpr int NGRP = 2, GSZ = NIT / NGRP;
;         __syncthreads();
; #pragma unroll 1
;         for (int gq = 0; gq < NGRP; ++gq) {
;             decltype(ld(0, 0)) fetched[GSZ];
; #pragma unroll
;             for (int c = 0; c < GSZ; ++c) {
;                 const int idx = tid + (gq * GSZ + c) * NT, lr = idx / NCH, ch = idx % NCH;
;                 fetched[c] = ld((lr >> 5) * 64 + jt * 32 + (lr & 31), ch * 8);
;             }
; #pragma unroll
;             for (int c = 0; c < GSZ; ++c) {
;                 const int idx = tid + (gq * GSZ + c) * NT, lr = idx / NCH, ch = idx % NCH;
;                 const u32x4 v = *(const u32x4*)(lds + lr * RS + ch * 16);
; DI void phase5(const Params& p, unsigned char* smem, int tid, bool coop) {
;     ...
;             staged_rows_rmw<4, 4>(lds, te,
;                 [&](int it, int jt, int g) { const f32x4 gv = *(const f32x4*)(p.post_g + f * 256 + wi * 128 + it * 32 + 8 * g + 4 * h); const float rs = rsj[jt];
;                     return pk4(acc[it][jt][4 * g] * rs * gv[0], acc[it][jt][4 * g + 1] * rs * gv[1], acc[it][jt][4 * g + 2] * rs * gv[2], acc[it][jt][4 * g + 3] * rs * gv[3]); },
;                 [&](int row, int col) { const size_t o = (size_t)(tt * 256 + row) * 1024 + f * 256 + col; X8 r; r.a = __builtin_nontemporal_load((const f32x4*)(p.x + o)); r.b = __builtin_nontemporal_load((const f32x4*)(p.x + o + 4)); return r; },
;                 [&](int row, int col, u32x4 v, X8 xv) { const size_t o = (size_t)(tt * 256 + row) * 1024 + f * 256 + col;
;                     __builtin_nontemporal_store((f32x4){xv.a[0] + bf_lo(v[0]), xv.a[1] + bf_hi(v[0]), xv.a[2] + bf_lo(v[1]), xv.a[3] + bf_hi(v[1])}, (f32x4*)(p.out + o));
;                     __builtin_nontemporal_store((f32x4){xv.b[0] + bf_lo(v[2]), xv.b[1] + bf_hi(v[2]), xv.b[2] + bf_lo(v[3]), xv.b[3] + bf_hi(v[3])}, (f32x4*)(p.out + o + 4)); });
	ds_read_b64 v[64:65], v246 offset:2048
	ds_read_b64 v[66:67], v246 offset:2576
	ds_read_b64 v[68:69], v246 offset:3104
	ds_read_b64 v[70:71], v246 offset:3632
	ds_read_b64 v[72:73], v246 offset:4160
	ds_read_b64 v[74:75], v246 offset:4688
	ds_read_b64 v[76:77], v246 offset:5216
	ds_read_b64 v[78:79], v246 offset:5744
	ds_read_b64 v[80:81], v246 offset:6272
	ds_read_b64 v[82:83], v246 offset:6800
	ds_read_b64 v[84:85], v246 offset:7328
	ds_read_b64 v[86:87], v246 offset:7856
	ds_read_b64 v[88:89], v246 offset:8384
	ds_read_b64 v[90:91], v246 offset:8912
	ds_read_b64 v[92:93], v246 offset:9440
	ds_read_b64 v[94:95], v246 offset:9968
	v_pk_mul_f32 v[48:49], v[48:49], v[144:145] op_sel_hi:[1,0]
	v_pk_mul_f32 v[50:51], v[50:51], v[144:145] op_sel_hi:[1,0]
	v_pk_mul_f32 v[52:53], v[52:53], v[144:145] op_sel_hi:[1,0]
	v_pk_mul_f32 v[54:55], v[54:55], v[144:145] op_sel_hi:[1,0]
	v_pk_mul_f32 v[56:57], v[56:57], v[144:145] op_sel_hi:[1,0]
	v_pk_mul_f32 v[58:59], v[58:59], v[144:145] op_sel_hi:[1,0]
	v_pk_mul_f32 v[60:61], v[60:61], v[144:145] op_sel_hi:[1,0]
	v_pk_mul_f32 v[62:63], v[62:63], v[144:145] op_sel_hi:[1,0]
	v_pk_mul_f32 v[32:33], v[32:33], v[144:145] op_sel_hi:[1,0]
	v_pk_mul_f32 v[34:35], v[34:35], v[144:145] op_sel_hi:[1,0]
	v_pk_mul_f32 v[36:37], v[36:37], v[144:145] op_sel_hi:[1,0]
	v_pk_mul_f32 v[38:39], v[38:39], v[144:145] op_sel_hi:[1,0]
	v_pk_mul_f32 v[40:41], v[40:41], v[144:145] op_sel_hi:[1,0]
	v_pk_mul_f32 v[42:43], v[42:43], v[144:145] op_sel_hi:[1,0]
	v_pk_mul_f32 v[44:45], v[44:45], v[144:145] op_sel_hi:[1,0]
	v_pk_mul_f32 v[46:47], v[46:47], v[144:145] op_sel_hi:[1,0]
	v_pk_mul_f32 v[16:17], v[16:17], v[144:145] op_sel_hi:[1,0]
	v_pk_mul_f32 v[18:19], v[18:19], v[144:145] op_sel_hi:[1,0]
	v_pk_mul_f32 v[20:21], v[20:21], v[144:145] op_sel_hi:[1,0]
	v_pk_mul_f32 v[22:23], v[22:23], v[144:145] op_sel_hi:[1,0]
	v_pk_mul_f32 v[24:25], v[24:25], v[144:145] op_sel_hi:[1,0]
	v_pk_mul_f32 v[26:27], v[26:27], v[144:145] op_sel_hi:[1,0]
	v_pk_mul_f32 v[28:29], v[28:29], v[144:145] op_sel_hi:[1,0]
	v_pk_mul_f32 v[30:31], v[30:31], v[144:145] op_sel_hi:[1,0]
	v_pk_mul_f32 v[0:1], v[0:1], v[144:145] op_sel_hi:[1,0]
	v_pk_mul_f32 v[2:3], v[2:3], v[144:145] op_sel_hi:[1,0]
	v_pk_mul_f32 v[4:5], v[4:5], v[144:145] op_sel_hi:[1,0]
	v_pk_mul_f32 v[6:7], v[6:7], v[144:145] op_sel_hi:[1,0]
	v_pk_mul_f32 v[8:9], v[8:9], v[144:145] op_sel_hi:[1,0]
	v_pk_mul_f32 v[10:11], v[10:11], v[144:145] op_sel_hi:[1,0]
	v_pk_mul_f32 v[12:13], v[12:13], v[144:145] op_sel_hi:[1,0]
	v_pk_mul_f32 v[14:15], v[14:15], v[144:145] op_sel_hi:[1,0]
	v_cvt_pk_bf16_f32 v48, v48, v49
	v_cvt_pk_bf16_f32 v49, v50, v51
	v_cvt_pk_bf16_f32 v52, v52, v53
	v_cvt_pk_bf16_f32 v53, v54, v55
	v_cvt_pk_bf16_f32 v56, v56, v57
	v_cvt_pk_bf16_f32 v57, v58, v59
	v_cvt_pk_bf16_f32 v60, v60, v61
	v_cvt_pk_bf16_f32 v61, v62, v63
	v_cvt_pk_bf16_f32 v32, v32, v33
	v_cvt_pk_bf16_f32 v33, v34, v35
	v_cvt_pk_bf16_f32 v36, v36, v37
	v_cvt_pk_bf16_f32 v37, v38, v39
	v_cvt_pk_bf16_f32 v40, v40, v41
	v_cvt_pk_bf16_f32 v41, v42, v43
	v_cvt_pk_bf16_f32 v44, v44, v45
	v_cvt_pk_bf16_f32 v45, v46, v47
	v_cvt_pk_bf16_f32 v16, v16, v17
	v_cvt_pk_bf16_f32 v17, v18, v19
	v_cvt_pk_bf16_f32 v20, v20, v21
	v_cvt_pk_bf16_f32 v21, v22, v23
	v_cvt_pk_bf16_f32 v24, v24, v25
	v_cvt_pk_bf16_f32 v25, v26, v27
	v_cvt_pk_bf16_f32 v28, v28, v29
	v_cvt_pk_bf16_f32 v29, v30, v31
	v_cvt_pk_bf16_f32 v0, v0, v1
	v_cvt_pk_bf16_f32 v1, v2, v3
	v_cvt_pk_bf16_f32 v4, v4, v5
	v_cvt_pk_bf16_f32 v5, v6, v7
	v_cvt_pk_bf16_f32 v8, v8, v9
	v_cvt_pk_bf16_f32 v9, v10, v11
	v_cvt_pk_bf16_f32 v12, v12, v13
	v_cvt_pk_bf16_f32 v13, v14, v15
	s_waitcnt lgkmcnt(0)
	s_barrier
	ds_write2_b64 v143, v[48:49], v[52:53] offset0:0 offset1:2
	ds_write2_b64 v143, v[56:57], v[60:61] offset0:4 offset1:6
	ds_write2_b64 v143, v[32:33], v[36:37] offset0:8 offset1:10
	ds_write2_b64 v143, v[40:41], v[44:45] offset0:12 offset1:14
	ds_write2_b64 v143, v[16:17], v[20:21] offset0:16 offset1:18
	ds_write2_b64 v143, v[24:25], v[28:29] offset0:20 offset1:22
	ds_write2_b64 v143, v[0:1], v[4:5] offset0:24 offset1:26
	ds_write2_b64 v143, v[8:9], v[12:13] offset0:28 offset1:30
	s_waitcnt lgkmcnt(0)
	s_barrier
	ds_read_b64 v[0:1], v246 offset:2048
	ds_read_b64 v[2:3], v246 offset:2576
	ds_read_b64 v[4:5], v246 offset:3104
	ds_read_b64 v[6:7], v246 offset:3632
	ds_read_b64 v[8:9], v246 offset:4160
	ds_read_b64 v[10:11], v246 offset:4688
	ds_read_b64 v[12:13], v246 offset:5216
	ds_read_b64 v[14:15], v246 offset:5744
	ds_read_b64 v[16:17], v246 offset:6272
	ds_read_b64 v[18:19], v246 offset:6800
	ds_read_b64 v[20:21], v246 offset:7328
	ds_read_b64 v[22:23], v246 offset:7856
	ds_read_b64 v[24:25], v246 offset:8384
	ds_read_b64 v[26:27], v246 offset:8912
	ds_read_b64 v[28:29], v246 offset:9440
	ds_read_b64 v[30:31], v246 offset:9968
	v_lshlrev_b32_e32 v96, 16, v64
	v_and_b32_e32 v97, 0xffff0000, v64
	v_lshlrev_b32_e32 v98, 16, v65
	v_and_b32_e32 v99, 0xffff0000, v65
	s_waitcnt vmcnt(23)
	v_pk_add_f32 v[218:219], v[218:219], v[96:97]
	v_pk_add_f32 v[220:221], v[220:221], v[98:99]
	v_add_u32_e32 v252, 0x1000, v254
	global_store_dwordx4 v252, v[218:221], s[6:7] offset:-4096 nt
	v_lshlrev_b32_e32 v100, 16, v66
	v_and_b32_e32 v101, 0xffff0000, v66
	v_lshlrev_b32_e32 v102, 16, v67
	v_and_b32_e32 v103, 0xffff0000, v67
	s_waitcnt vmcnt(23)
	v_pk_add_f32 v[222:223], v[222:223], v[100:101]
	v_pk_add_f32 v[224:225], v[224:225], v[102:103]
	global_store_dwordx4 v252, v[222:225], s[6:7] nt
	v_lshlrev_b32_e32 v96, 16, v68
	v_and_b32_e32 v97, 0xffff0000, v68
	v_lshlrev_b32_e32 v98, 16, v69
	v_and_b32_e32 v99, 0xffff0000, v69
	s_waitcnt vmcnt(23)
; DI float bf_lo(unsigned u) { return __uint_as_float(u << 16); }
; DI float bf_hi(unsigned u) { return __uint_as_float(u & 0xffff0000u); }
; template <int WI, int WGJ, class GetF, class LdF, class FinF>
; DI void staged_rows_rmw(unsigned char* lds, int tid, GetF get, LdF ld, FinF fin) {
;     ...
;             for (int c = 0; c < GSZ; ++c) {
;                 const int idx = tid + (gq * GSZ + c) * NT, lr = idx / NCH, ch = idx % NCH;
;                 fetched[c] = ld((lr >> 5) * 64 + jt * 32 + (lr & 31), ch * 8);
;             }
; #pragma unroll
;             for (int c = 0; c < GSZ; ++c) {
;                 const int idx = tid + (gq * GSZ + c) * NT, lr = idx / NCH, ch = idx % NCH;
;                 const u32x4 v = *(const u32x4*)(lds + lr * RS + ch * 16);
;                 fin((lr >> 5) * 64 + jt * 32 + (lr & 31), ch * 8, v, fetched[c]);
;             }
; DI void phase5(const Params& p, unsigned char* smem, int tid, bool coop) {
;     ...
;                 [&](int row, int col) { const size_t o = (size_t)(tt * 256 + row) * 1024 + f * 256 + col; X8 r; r.a = __builtin_nontemporal_load((const f32x4*)(p.x + o)); r.b = __builtin_nontemporal_load((const f32x4*)(p.x + o + 4)); return r; },
;                 [&](int row, int col, u32x4 v, X8 xv) { const size_t o = (size_t)(tt * 256 + row) * 1024 + f * 256 + col;
;                     __builtin_nontemporal_store((f32x4){xv.a[0] + bf_lo(v[0]), xv.a[1] + bf_hi(v[0]), xv.a[2] + bf_lo(v[1]), xv.a[3] + bf_hi(v[1])}, (f32x4*)(p.out + o));
;                     __builtin_nontemporal_store((f32x4){xv.b[0] + bf_lo(v[2]), xv.b[1] + bf_hi(v[2]), xv.b[2] + bf_lo(v[3]), xv.b[3] + bf_hi(v[3])}, (f32x4*)(p.out + o + 4)); });
	v_pk_add_f32 v[226:227], v[226:227], v[96:97]
	v_pk_add_f32 v[228:229], v[228:229], v[98:99]
	v_add_u32_e32 v253, 0x3000, v254
	global_store_dwordx4 v253, v[226:229], s[6:7] offset:-4096 nt
	v_lshlrev_b32_e32 v100, 16, v70
	v_and_b32_e32 v101, 0xffff0000, v70
	v_lshlrev_b32_e32 v102, 16, v71
	v_and_b32_e32 v103, 0xffff0000, v71
	s_waitcnt vmcnt(23)
	v_pk_add_f32 v[230:231], v[230:231], v[100:101]
	v_pk_add_f32 v[232:233], v[232:233], v[102:103]
	global_store_dwordx4 v253, v[230:233], s[6:7] nt
	v_lshlrev_b32_e32 v96, 16, v72
	v_and_b32_e32 v97, 0xffff0000, v72
	v_lshlrev_b32_e32 v98, 16, v73
	v_and_b32_e32 v99, 0xffff0000, v73
	s_waitcnt vmcnt(23)
	v_pk_add_f32 v[234:235], v[234:235], v[96:97]
	v_pk_add_f32 v[236:237], v[236:237], v[98:99]
	v_add_u32_e32 v252, 0x5000, v254
	global_store_dwordx4 v252, v[234:237], s[6:7] offset:-4096 nt
	v_lshlrev_b32_e32 v100, 16, v74
	v_and_b32_e32 v101, 0xffff0000, v74
	v_lshlrev_b32_e32 v102, 16, v75
	v_and_b32_e32 v103, 0xffff0000, v75
	s_waitcnt vmcnt(23)
	v_pk_add_f32 v[238:239], v[238:239], v[100:101]
	v_pk_add_f32 v[240:241], v[240:241], v[102:103]
	global_store_dwordx4 v252, v[238:241], s[6:7] nt
	v_lshlrev_b32_e32 v96, 16, v76
	v_and_b32_e32 v97, 0xffff0000, v76
	v_lshlrev_b32_e32 v98, 16, v77
	v_and_b32_e32 v99, 0xffff0000, v77
	s_waitcnt vmcnt(23)
	v_pk_add_f32 v[242:243], v[242:243], v[96:97]
	v_pk_add_f32 v[244:245], v[244:245], v[98:99]
	v_add_u32_e32 v253, 0x7000, v254
	global_store_dwordx4 v253, v[242:245], s[6:7] offset:-4096 nt
	v_lshlrev_b32_e32 v100, 16, v78
	v_and_b32_e32 v101, 0xffff0000, v78
	v_lshlrev_b32_e32 v102, 16, v79
	v_and_b32_e32 v103, 0xffff0000, v79
	s_waitcnt vmcnt(23)
	v_pk_add_f32 v[248:249], v[248:249], v[100:101]
	v_pk_add_f32 v[250:251], v[250:251], v[102:103]
	global_store_dwordx4 v253, v[248:251], s[6:7] nt
	v_add_u32_e32 v252, 0x29000, v254
	global_load_dwordx4 v[218:221], v252, s[100:101] offset:-4096 nt
	global_load_dwordx4 v[222:225], v252, s[100:101] nt
	v_add_u32_e32 v253, 0x2b000, v254
	global_load_dwordx4 v[226:229], v253, s[100:101] offset:-4096 nt
	global_load_dwordx4 v[230:233], v253, s[100:101] nt
	v_add_u32_e32 v252, 0x2d000, v254
	global_load_dwordx4 v[234:237], v252, s[100:101] offset:-4096 nt
	global_load_dwordx4 v[238:241], v252, s[100:101] nt
	v_add_u32_e32 v253, 0x2f000, v254
	global_load_dwordx4 v[242:245], v253, s[100:101] offset:-4096 nt
	global_load_dwordx4 v[248:251], v253, s[100:101] nt
	v_lshlrev_b32_e32 v96, 16, v80
	v_and_b32_e32 v97, 0xffff0000, v80
	v_lshlrev_b32_e32 v98, 16, v81
	v_and_b32_e32 v99, 0xffff0000, v81
	s_waitcnt vmcnt(31)
	v_pk_add_f32 v[146:147], v[146:147], v[96:97]
	v_pk_add_f32 v[148:149], v[148:149], v[98:99]
	v_add_u32_e32 v252, 0x9000, v254
	global_store_dwordx4 v252, v[146:149], s[6:7] offset:-4096 nt
	v_lshlrev_b32_e32 v100, 16, v82
	v_and_b32_e32 v101, 0xffff0000, v82
	v_lshlrev_b32_e32 v102, 16, v83
	v_and_b32_e32 v103, 0xffff0000, v83
	s_waitcnt vmcnt(31)
	v_pk_add_f32 v[150:151], v[150:151], v[100:101]
	v_pk_add_f32 v[152:153], v[152:153], v[102:103]
	global_store_dwordx4 v252, v[150:153], s[6:7] nt
	v_lshlrev_b32_e32 v96, 16, v84
	v_and_b32_e32 v97, 0xffff0000, v84
	v_lshlrev_b32_e32 v98, 16, v85
	v_and_b32_e32 v99, 0xffff0000, v85
	s_waitcnt vmcnt(31)
	v_pk_add_f32 v[154:155], v[154:155], v[96:97]
	v_pk_add_f32 v[156:157], v[156:157], v[98:99]
	v_add_u32_e32 v253, 0xb000, v254
	global_store_dwordx4 v253, v[154:157], s[6:7] offset:-4096 nt
	v_lshlrev_b32_e32 v100, 16, v86
	v_and_b32_e32 v101, 0xffff0000, v86
	v_lshlrev_b32_e32 v102, 16, v87
	v_and_b32_e32 v103, 0xffff0000, v87
	s_waitcnt vmcnt(31)
	v_pk_add_f32 v[158:159], v[158:159], v[100:101]
	v_pk_add_f32 v[160:161], v[160:161], v[102:103]
	global_store_dwordx4 v253, v[158:161], s[6:7] nt
	v_lshlrev_b32_e32 v96, 16, v88
	v_and_b32_e32 v97, 0xffff0000, v88
	v_lshlrev_b32_e32 v98, 16, v89
	v_and_b32_e32 v99, 0xffff0000, v89
	s_waitcnt vmcnt(31)
	v_pk_add_f32 v[162:163], v[162:163], v[96:97]
	v_pk_add_f32 v[164:165], v[164:165], v[98:99]
	v_add_u32_e32 v252, 0xd000, v254
	global_store_dwordx4 v252, v[162:165], s[6:7] offset:-4096 nt
	v_lshlrev_b32_e32 v100, 16, v90
	v_and_b32_e32 v101, 0xffff0000, v90
	v_lshlrev_b32_e32 v102, 16, v91
	v_and_b32_e32 v103, 0xffff0000, v91
	s_waitcnt vmcnt(31)
	v_pk_add_f32 v[166:167], v[166:167], v[100:101]
	v_pk_add_f32 v[168:169], v[168:169], v[102:103]
	global_store_dwordx4 v252, v[166:169], s[6:7] nt
	v_lshlrev_b32_e32 v96, 16, v92
	v_and_b32_e32 v97, 0xffff0000, v92
	v_lshlrev_b32_e32 v98, 16, v93
	v_and_b32_e32 v99, 0xffff0000, v93
	s_waitcnt vmcnt(31)
	v_pk_add_f32 v[170:171], v[170:171], v[96:97]
	v_pk_add_f32 v[172:173], v[172:173], v[98:99]
	v_add_u32_e32 v253, 0xf000, v254
	global_store_dwordx4 v253, v[170:173], s[6:7] offset:-4096 nt
	v_lshlrev_b32_e32 v100, 16, v94
	v_and_b32_e32 v101, 0xffff0000, v94
	v_lshlrev_b32_e32 v102, 16, v95
	v_and_b32_e32 v103, 0xffff0000, v95
	s_waitcnt vmcnt(31)
	v_pk_add_f32 v[174:175], v[174:175], v[100:101]
	v_pk_add_f32 v[176:177], v[176:177], v[102:103]
	global_store_dwordx4 v253, v[174:177], s[6:7] nt
	s_waitcnt lgkmcnt(0)
	v_lshlrev_b32_e32 v96, 16, v0
	v_and_b32_e32 v97, 0xffff0000, v0
	v_lshlrev_b32_e32 v98, 16, v1
	v_and_b32_e32 v99, 0xffff0000, v1
	s_waitcnt vmcnt(31)
; DI float bf_lo(unsigned u) { return __uint_as_float(u << 16); }
; DI float bf_hi(unsigned u) { return __uint_as_float(u & 0xffff0000u); }
; template <int WI, int WGJ, class GetF, class LdF, class FinF>
; DI void staged_rows_rmw(unsigned char* lds, int tid, GetF get, LdF ld, FinF fin) {
;     ...
;             for (int c = 0; c < GSZ; ++c) {
;                 const int idx = tid + (gq * GSZ + c) * NT, lr = idx / NCH, ch = idx % NCH;
;                 const u32x4 v = *(const u32x4*)(lds + lr * RS + ch * 16);
;                 fin((lr >> 5) * 64 + jt * 32 + (lr & 31), ch * 8, v, fetched[c]);
;             }
; DI void phase5(const Params& p, unsigned char* smem, int tid, bool coop) {
;     ...
;                 [&](int row, int col, u32x4 v, X8 xv) { const size_t o = (size_t)(tt * 256 + row) * 1024 + f * 256 + col;
;                     __builtin_nontemporal_store((f32x4){xv.a[0] + bf_lo(v[0]), xv.a[1] + bf_hi(v[0]), xv.a[2] + bf_lo(v[1]), xv.a[3] + bf_hi(v[1])}, (f32x4*)(p.out + o));
;                     __builtin_nontemporal_store((f32x4){xv.b[0] + bf_lo(v[2]), xv.b[1] + bf_hi(v[2]), xv.b[2] + bf_lo(v[3]), xv.b[3] + bf_hi(v[3])}, (f32x4*)(p.out + o + 4)); });
	v_pk_add_f32 v[178:179], v[178:179], v[96:97]
	v_pk_add_f32 v[180:181], v[180:181], v[98:99]
	v_add_u32_e32 v252, 0x21000, v254
	global_store_dwordx4 v252, v[178:181], s[6:7] offset:-4096 nt
	v_lshlrev_b32_e32 v100, 16, v2
	v_and_b32_e32 v101, 0xffff0000, v2
	v_lshlrev_b32_e32 v102, 16, v3
	v_and_b32_e32 v103, 0xffff0000, v3
	s_waitcnt vmcnt(31)
	v_pk_add_f32 v[186:187], v[186:187], v[100:101]
	v_pk_add_f32 v[188:189], v[188:189], v[102:103]
	global_store_dwordx4 v252, v[186:189], s[6:7] nt
	v_lshlrev_b32_e32 v96, 16, v4
	v_and_b32_e32 v97, 0xffff0000, v4
	v_lshlrev_b32_e32 v98, 16, v5
	v_and_b32_e32 v99, 0xffff0000, v5
	s_waitcnt vmcnt(31)
	v_pk_add_f32 v[190:191], v[190:191], v[96:97]
	v_pk_add_f32 v[192:193], v[192:193], v[98:99]
	v_add_u32_e32 v253, 0x23000, v254
	global_store_dwordx4 v253, v[190:193], s[6:7] offset:-4096 nt
	v_lshlrev_b32_e32 v100, 16, v6
	v_and_b32_e32 v101, 0xffff0000, v6
	v_lshlrev_b32_e32 v102, 16, v7
	v_and_b32_e32 v103, 0xffff0000, v7
	s_waitcnt vmcnt(31)
	v_pk_add_f32 v[198:199], v[198:199], v[100:101]
	v_pk_add_f32 v[200:201], v[200:201], v[102:103]
	global_store_dwordx4 v253, v[198:201], s[6:7] nt
	v_lshlrev_b32_e32 v96, 16, v8
	v_and_b32_e32 v97, 0xffff0000, v8
	v_lshlrev_b32_e32 v98, 16, v9
	v_and_b32_e32 v99, 0xffff0000, v9
	s_waitcnt vmcnt(31)
	v_pk_add_f32 v[202:203], v[202:203], v[96:97]
	v_pk_add_f32 v[204:205], v[204:205], v[98:99]
	v_add_u32_e32 v252, 0x25000, v254
	global_store_dwordx4 v252, v[202:205], s[6:7] offset:-4096 nt
	v_lshlrev_b32_e32 v100, 16, v10
	v_and_b32_e32 v101, 0xffff0000, v10
	v_lshlrev_b32_e32 v102, 16, v11
	v_and_b32_e32 v103, 0xffff0000, v11
	s_waitcnt vmcnt(31)
	v_pk_add_f32 v[206:207], v[206:207], v[100:101]
	v_pk_add_f32 v[208:209], v[208:209], v[102:103]
	global_store_dwordx4 v252, v[206:209], s[6:7] nt
	v_lshlrev_b32_e32 v96, 16, v12
	v_and_b32_e32 v97, 0xffff0000, v12
	v_lshlrev_b32_e32 v98, 16, v13
	v_and_b32_e32 v99, 0xffff0000, v13
	s_waitcnt vmcnt(31)
	v_pk_add_f32 v[210:211], v[210:211], v[96:97]
	v_pk_add_f32 v[212:213], v[212:213], v[98:99]
	v_add_u32_e32 v253, 0x27000, v254
	global_store_dwordx4 v253, v[210:213], s[6:7] offset:-4096 nt
	v_lshlrev_b32_e32 v100, 16, v14
	v_and_b32_e32 v101, 0xffff0000, v14
	v_lshlrev_b32_e32 v102, 16, v15
	v_and_b32_e32 v103, 0xffff0000, v15
	s_waitcnt vmcnt(31)
	v_pk_add_f32 v[214:215], v[214:215], v[100:101]
	v_pk_add_f32 v[216:217], v[216:217], v[102:103]
	global_store_dwordx4 v253, v[214:217], s[6:7] nt
	v_lshlrev_b32_e32 v96, 16, v16
	v_and_b32_e32 v97, 0xffff0000, v16
	v_lshlrev_b32_e32 v98, 16, v17
	v_and_b32_e32 v99, 0xffff0000, v17
	s_waitcnt vmcnt(23)
	v_pk_add_f32 v[218:219], v[218:219], v[96:97]
	v_pk_add_f32 v[220:221], v[220:221], v[98:99]
	v_add_u32_e32 v252, 0x29000, v254
	global_store_dwordx4 v252, v[218:221], s[6:7] offset:-4096 nt
	v_lshlrev_b32_e32 v100, 16, v18
	v_and_b32_e32 v101, 0xffff0000, v18
	v_lshlrev_b32_e32 v102, 16, v19
	v_and_b32_e32 v103, 0xffff0000, v19
	s_waitcnt vmcnt(23)
	v_pk_add_f32 v[222:223], v[222:223], v[100:101]
	v_pk_add_f32 v[224:225], v[224:225], v[102:103]
	global_store_dwordx4 v252, v[222:225], s[6:7] nt
	v_lshlrev_b32_e32 v96, 16, v20
	v_and_b32_e32 v97, 0xffff0000, v20
	v_lshlrev_b32_e32 v98, 16, v21
	v_and_b32_e32 v99, 0xffff0000, v21
	s_waitcnt vmcnt(23)
	v_pk_add_f32 v[226:227], v[226:227], v[96:97]
	v_pk_add_f32 v[228:229], v[228:229], v[98:99]
	v_add_u32_e32 v253, 0x2b000, v254
	global_store_dwordx4 v253, v[226:229], s[6:7] offset:-4096 nt
	v_lshlrev_b32_e32 v100, 16, v22
	v_and_b32_e32 v101, 0xffff0000, v22
	v_lshlrev_b32_e32 v102, 16, v23
	v_and_b32_e32 v103, 0xffff0000, v23
	s_waitcnt vmcnt(23)
	v_pk_add_f32 v[230:231], v[230:231], v[100:101]
	v_pk_add_f32 v[232:233], v[232:233], v[102:103]
	global_store_dwordx4 v253, v[230:233], s[6:7] nt
	v_lshlrev_b32_e32 v96, 16, v24
	v_and_b32_e32 v97, 0xffff0000, v24
	v_lshlrev_b32_e32 v98, 16, v25
	v_and_b32_e32 v99, 0xffff0000, v25
	s_waitcnt vmcnt(23)
	v_pk_add_f32 v[234:235], v[234:235], v[96:97]
	v_pk_add_f32 v[236:237], v[236:237], v[98:99]
	v_add_u32_e32 v252, 0x2d000, v254
	global_store_dwordx4 v252, v[234:237], s[6:7] offset:-4096 nt
	v_lshlrev_b32_e32 v100, 16, v26
	v_and_b32_e32 v101, 0xffff0000, v26
	v_lshlrev_b32_e32 v102, 16, v27
	v_and_b32_e32 v103, 0xffff0000, v27
	s_waitcnt vmcnt(23)
	v_pk_add_f32 v[238:239], v[238:239], v[100:101]
	v_pk_add_f32 v[240:241], v[240:241], v[102:103]
	global_store_dwordx4 v252, v[238:241], s[6:7] nt
	v_lshlrev_b32_e32 v96, 16, v28
	v_and_b32_e32 v97, 0xffff0000, v28
	v_lshlrev_b32_e32 v98, 16, v29
	v_and_b32_e32 v99, 0xffff0000, v29
	s_waitcnt vmcnt(23)
	v_pk_add_f32 v[242:243], v[242:243], v[96:97]
	v_pk_add_f32 v[244:245], v[244:245], v[98:99]
	v_add_u32_e32 v253, 0x2f000, v254
	global_store_dwordx4 v253, v[242:245], s[6:7] offset:-4096 nt
	v_lshlrev_b32_e32 v100, 16, v30
	v_and_b32_e32 v101, 0xffff0000, v30
	v_lshlrev_b32_e32 v102, 16, v31
	v_and_b32_e32 v103, 0xffff0000, v31
	s_waitcnt vmcnt(23)
	v_pk_add_f32 v[248:249], v[248:249], v[100:101]
	v_pk_add_f32 v[250:251], v[250:251], v[102:103]
	global_store_dwordx4 v253, v[248:251], s[6:7] nt
	s_barrier
	s_branch .LBB0_1057
